# trim VALU overhead in selected-branch attention fast path (branch-free accumulator init, in-place softmax state, scalar buffer toggle)
# speedup vs baseline: 1.0102x; 1.0020x over previous
; template <int MODE>
; __device__ __forceinline__ void attn_branch(AttnState& st, const bf16_t* __restrict__ Kg, const bf16_t* __restrict__ Vg, u64 tiles, LAS bf16_t* KsB, LAS bf16_t* VtB,
;                                             int tq, u64 mymask, int cur, int fr, int fq, float (&imp)[16]) {
;     ...
;     if (tiles == 0ull) return;
;     int jb = __builtin_ctzll(tiles); tiles &= tiles - 1ull;
;     u32x4v kr = *(const u32x4v*)(Kg + (size_t)(jb * 64 + kkey) * 64 + kch * 8), vr = (u32x4v){0u, 0u, 0u, 0u};
; __device__ __forceinline__ void attn_phase(const Args& a, LAS unsigned char* lds) {
;     ...
;             u32x4v qvl[2][2];
; #pragma unroll
;             for (int ct = 0; ct < 2; ++ct)
; #pragma unroll
;                 for (int kk = 0; kk < 2; ++kk) { const int hq = g * 4 + 2 * ct + (fr >> 3); qvl[ct][kk] = *(const u32x4v*)(Q + row * 512 + hq * 64 + kk * 32 + fq * 8); }
;             float cs[8], sn[8];
; #pragma unroll
;             for (int e = 0; e < 8; ++e) { cs[e] = RT[(tq * 8 + e) * 2]; sn[e] = RT[(tq * 8 + e) * 2 + 1]; }
; #pragma unroll
;             for (int ct = 0; ct < 2; ++ct)
; #pragma unroll
;                 for (int kk = 0; kk < 2; ++kk) {
;                     const u32x4v qv = qvl[ct][kk];
;                     const unsigned qw[4] = {qv.x, qv.y, qv.z, qv.w};
;                     float r[8];
; #pragma unroll
;                     for (int e = 0; e < 8; ++e) {
;                         const float x = (e & 1) ? __uint_as_float(qw[e >> 1] & 0xffff0000u) : __uint_as_float(qw[e >> 1] << 16);
;                         if (kk == 0) { const float ot = __shfl_xor(x, 16); r[e] = (fq == 0 ? x * cs[e] - ot * sn[e] : (fq == 1 ? x * cs[e] + ot * sn[e] : x)) * ATT_QS; }
;                         else r[e] = x * ATT_QS;
;                     }
;                     u32x4v o; o.x = cvt_pk_bf16(r[0], r[1]); o.y = cvt_pk_bf16(r[2], r[3]); o.z = cvt_pk_bf16(r[4], r[5]); o.w = cvt_pk_bf16(r[6], r[7]);
;                     st.qf[ct][kk] = __builtin_bit_cast(bf16x8, o);
;                 }
;         }
; #pragma unroll
;         for (int ct = 0; ct < 2; ++ct) { st.m[ct] = -1e30f; st.l[ct] = 0.f;
; #pragma unroll
;             for (int dt = 0; dt < 4; ++dt) st.o[ct][dt] = (f32x4){0.f, 0.f, 0.f, 0.f}; }
;         attn_branch<M_SLC>(st, KV + 2 * KVSZ + (size_t)bg * 4096 * 64, KV + 3 * KVSZ + (size_t)bg * 4096 * 64, bun, Ks, Vt, tq, mymask, cur, fr, fq, imp);
.LBB0_1126:
	s_or_b64 exec, exec, s[16:17]
	s_waitcnt lgkmcnt(3)
	v_mul_f32_e32 v25, 0x3e38aa3b, v12
	v_mul_f32_e32 v12, 0x3e38aa3b, v42
	v_mul_f32_e32 v13, 0x3e38aa3b, v40
	v_mul_f32_e32 v4, 0x3e38aa3b, v36
	v_mul_f32_e32 v6, 0x3e38aa3b, v6
	v_mul_f32_e32 v7, 0x3e38aa3b, v44
	v_mul_f32_e32 v5, 0x3e38aa3b, v32
	v_mul_f32_e32 v14, 0x3e38aa3b, v38
	v_mul_f32_e32 v15, 0x3e38aa3b, v34
	v_cvt_pk_bf16_f32 v4, v6, v4
	v_cvt_pk_bf16_f32 v6, v13, v12
	v_lshlrev_b32_e32 v12, 16, v8
	v_and_b32_e32 v13, 0xffff0000, v8
	s_mov_b32 s16, 0x3e38aa3b
	v_lshlrev_b32_e32 v8, 16, v9
	v_and_b32_e32 v9, 0xffff0000, v9
	s_or_b64 s[2:3], s[4:5], s[2:3]
	v_cvt_pk_bf16_f32 v5, v14, v5
	v_cvt_pk_bf16_f32 v7, v7, v15
	v_pk_mul_f32 v[14:15], v[8:9], s[16:17] op_sel_hi:[1,0]
	v_lshlrev_b32_e32 v8, 16, v10
	v_and_b32_e32 v9, 0xffff0000, v10
	s_or_b64 s[2:3], s[2:3], s[6:7]
	v_mul_f32_e32 v0, 0x3e38aa3b, v22
	s_waitcnt lgkmcnt(0)
	v_mul_f32_e32 v3, 0x3e38aa3b, v20
	v_mul_f32_e32 v24, 0x3e38aa3b, v24
	v_pk_mul_f32 v[20:21], v[8:9], s[16:17] op_sel_hi:[1,0]
	v_lshlrev_b32_e32 v8, 16, v11
	v_and_b32_e32 v9, 0xffff0000, v11
	s_or_b64 s[2:3], s[2:3], s[8:9]
	v_mul_f32_e32 v2, 0x3e38aa3b, v2
	v_pk_mul_f32 v[22:23], v[8:9], s[16:17] op_sel_hi:[1,0]
	v_cvt_pk_bf16_f32 v9, v14, v15
	s_or_b64 s[2:3], s[2:3], s[10:11]
	v_cvt_pk_bf16_f32 v14, v24, v3
	v_cvt_pk_bf16_f32 v15, v0, v2
	v_lshlrev_b32_e32 v2, 16, v16
	v_and_b32_e32 v3, 0xffff0000, v16
	v_lshlrev_b32_e32 v16, 16, v17
	v_and_b32_e32 v17, 0xffff0000, v17
	v_cvt_pk_bf16_f32 v10, v20, v21
	s_or_b64 s[2:3], s[2:3], s[12:13]
	v_pk_mul_f32 v[20:21], v[16:17], s[16:17] op_sel_hi:[1,0]
	v_lshlrev_b32_e32 v16, 16, v18
	v_and_b32_e32 v17, 0xffff0000, v18
	v_mul_f32_e32 v26, 0x3e38aa3b, v30
	v_pk_mul_f32 v[12:13], v[12:13], s[16:17] op_sel_hi:[1,0]
	v_cvt_pk_bf16_f32 v11, v22, v23
	s_or_b64 s[2:3], s[2:3], s[14:15]
	v_pk_mul_f32 v[22:23], v[16:17], s[16:17] op_sel_hi:[1,0]
	v_lshlrev_b32_e32 v16, 16, v19
	v_and_b32_e32 v17, 0xffff0000, v19
	v_mul_f32_e32 v27, 0x3e38aa3b, v28
	v_mul_f32_e32 v28, 0x3e38aa3b, v46
	v_cvt_pk_bf16_f32 v8, v12, v13
	v_cvt_pk_bf16_f32 v13, v26, v25
	v_pk_mul_f32 v[2:3], v[2:3], s[16:17] op_sel_hi:[1,0]
	v_pk_mul_f32 v[24:25], v[16:17], s[16:17] op_sel_hi:[1,0]
	s_or_b64 s[0:1], s[2:3], s[0:1]
	s_lshl_b32 s14, s40, 18
	v_cvt_pk_bf16_f32 v12, v28, v27
	v_cvt_pk_bf16_f32 v16, v2, v3
	v_cvt_pk_bf16_f32 v17, v20, v21
	v_cvt_pk_bf16_f32 v18, v22, v23
	v_cvt_pk_bf16_f32 v19, v24, v25
	v_mov_b32_e32 v0, v199
	s_cmp_eq_u64 s[0:1], 0
	s_cbranch_scc1 .LBB0_1161
	s_lshl_b32 s4, s14, 1
	v_readlane_b32 s2, v252, 23
	s_add_u32 s2, s2, s4
	v_readlane_b32 s3, v252, 24
	s_addc_u32 s3, s3, 0
	v_readlane_b32 s5, v252, 25
	s_add_u32 s6, s5, s4
	v_readlane_b32 s4, v252, 26
	v_ashrrev_i32_e32 v187, 3, v0
	s_addc_u32 s7, s4, 0
	s_ff1_i32_b64 s4, s[0:1]
	v_lshl_add_u32 v2, s4, 6, v187
	v_ashrrev_i32_e32 v3, 31, v2
	v_lshlrev_b32_e32 v0, 3, v0
	v_lshlrev_b64 v[2:3], 7, v[2:3]
	v_and_b32_e32 v0, 56, v0
	v_lshl_add_u64 v[20:21], s[6:7], 0, v[2:3]
	v_lshlrev_b32_e32 v0, 1, v0
	v_lshl_add_u64 v[20:21], v[20:21], 0, v[0:1]
	v_lshl_add_u64 v[2:3], s[2:3], 0, v[2:3]
	v_lshl_add_u64 v[2:3], v[2:3], 0, v[0:1]
	global_load_dwordx4 v[36:39], v[20:21], off
	global_load_dwordx4 v[40:43], v[2:3], off
	v_or_b32_e32 v21, s39, v126
	v_or_b32_e32 v22, 2, v21
	v_cmp_le_i32_e64 s[42:43], v22, v152
	v_or_b32_e32 v22, 3, v21
	v_cmp_le_i32_e64 s[44:45], v22, v152
	v_or_b32_e32 v22, 16, v21
	v_cmp_le_i32_e64 s[46:47], v22, v152
	v_or_b32_e32 v22, 17, v21
	v_cmp_le_i32_e64 s[48:49], v22, v152
	v_or_b32_e32 v22, 18, v21
	v_cmp_le_i32_e64 s[50:51], v22, v152
	v_or_b32_e32 v22, 19, v21
	v_cmp_le_i32_e64 s[52:53], v22, v152
	v_or_b32_e32 v22, 32, v21
	v_cmp_le_i32_e64 s[54:55], v22, v152
	v_or_b32_e32 v22, 33, v21
	v_cmp_le_i32_e64 s[56:57], v22, v152
	v_or_b32_e32 v22, 34, v21
	v_cmp_le_i32_e64 s[58:59], v22, v152
	v_or_b32_e32 v22, 35, v21
	v_cmp_le_i32_e64 s[60:61], v22, v152
	v_or_b32_e32 v22, 48, v21
	s_movk_i32 s5, 0x48
	v_cmp_le_i32_e64 s[62:63], v22, v152
	v_or_b32_e32 v22, 49, v21
	s_add_u32 s8, s0, -1
	v_mul_lo_u32 v20, v187, s5
	v_cmp_le_i32_e64 s[64:65], v22, v152
	v_or_b32_e32 v22, 50, v21
	v_or_b32_e32 v21, 51, v21
	v_mov_b32_e32 v44, v1
	v_mov_b32_e32 v45, v1
	v_mov_b32_e32 v46, v1
	v_mov_b32_e32 v47, v1
	s_addc_u32 s9, s1, -1
	v_cmp_le_i32_e64 s[66:67], v22, v152
	v_cmp_le_i32_e64 s[68:69], v21, v152
	v_mov_b32_e32 v158, 0
	v_lshlrev_b32_e32 v189, 1, v20
	v_mov_b64_e32 v[50:51], v[46:47]
	v_mov_b64_e32 v[54:55], v[46:47]
	v_mov_b64_e32 v[58:59], v[46:47]
	v_mov_b64_e32 v[28:29], v[44:45]
	v_mov_b64_e32 v[32:33], v[44:45]
	v_mov_b64_e32 v[24:25], v[44:45]
	v_mov_b64_e32 v[20:21], v[44:45]
	s_and_b64 s[0:1], s[8:9], s[0:1]
	v_lshl_add_u64 v[2:3], s[6:7], 0, v[0:1]
	v_lshl_add_u64 v[160:161], s[2:3], 0, v[0:1]
	s_mov_b32 s15, 0
	v_mov_b32_e32 v190, 0xf149f2ca
	v_mov_b32_e32 v188, 0
	v_mov_b32_e32 v193, 0
	v_mov_b32_e32 v191, 0xf149f2ca
	v_mov_b64_e32 v[48:49], v[44:45]
	v_mov_b64_e32 v[52:53], v[44:45]
	v_mov_b64_e32 v[56:57], v[44:45]
	v_mov_b64_e32 v[30:31], v[46:47]
	v_mov_b64_e32 v[34:35], v[46:47]
	v_mov_b64_e32 v[26:27], v[46:47]
	v_mov_b64_e32 v[22:23], v[46:47]
	v_mov_b32_e32 v159, v158
.LBB0_1128:
	s_mul_i32 s2, s15, 0x2400
	s_add_i32 s17, s2, 0
	v_add3_u32 v60, v193, v189, v0
	s_waitcnt vmcnt(1)
	ds_write_b128 v60, v[36:39]
	v_add3_u32 v60, s17, v189, v0
	s_cmp_eq_u64 s[0:1], 0
	s_mov_b64 s[2:3], 0
	s_waitcnt vmcnt(0)
	ds_write_b128 v60, v[40:43] offset:18432
	s_cbranch_scc1 .LBB0_1130
	s_ff1_i32_b64 s16, s[0:1]
	v_lshl_add_u32 v36, s16, 6, v187
	v_ashrrev_i32_e32 v37, 31, v36
	v_lshlrev_b64 v[36:37], 7, v[36:37]
	v_lshl_add_u64 v[38:39], v[2:3], 0, v[36:37]
	v_lshl_add_u64 v[40:41], v[160:161], 0, v[36:37]
	global_load_dwordx4 v[36:39], v[38:39], off
	s_nop 0
	global_load_dwordx4 v[40:43], v[40:41], off
	s_add_u32 s2, s0, -1
	s_addc_u32 s3, s1, -1
	s_and_b64 s[2:3], s[2:3], s[0:1]
	s_branch .LBB0_1131

; #define LAS __attribute__((address_space(3)))
; template <int MODE, bool FAST, bool DEFER>
; __device__ __forceinline__ void attn_tile(AttnState& st, const LAS bf16_t* Ks, const LAS bf16_t* Vt, int jb, int tq, bool mybit, int fr, int fq, float (&imp)[16], float& prev_t3, bf16x8 (&pfo)[2][2]) {
;     ...
;     for (int ct = 0; ct < 2; ++ct) { const float nb_ = !FAST ? 0.f : ((MODE == M_SLC && !mybit) ? -1e30f : (st.m[ct] < -1e29f ? 0.f : -st.m[ct])); zinit[ct] = (f32x4){nb_, nb_, nb_, nb_}; }
; #pragma unroll
;     for (int sb = 0; sb < 4; ++sb) {
;         const bf16x8 k0 = *(const LAS bf16x8*)(Ks + (sb * 16 + fr) * KSTR + fq * 8);
;         const bf16x8 k1 = *(const LAS bf16x8*)(Ks + (sb * 16 + fr) * KSTR + 32 + fq * 8);
; #pragma unroll
;         for (int ct = 0; ct < 2; ++ct) {
;             f32x4 z = zinit[ct];
;             z = __builtin_amdgcn_mfma_f32_16x16x32_bf16(k0, st.qf[ct][0], z, 0, 0, 0);
;             z = __builtin_amdgcn_mfma_f32_16x16x32_bf16(k1, st.qf[ct][1], z, 0, 0, 0);
;             s[ct][sb] = ISCMP ? z * ATT_QS : z;
;         }
;     }
;     ...
;     if (FAST) {
;         float tz[2]; bool nd[2]; bool un[2];
; #pragma unroll
;         for (int ct = 0; ct < 2; ++ct) {
;             float t = -1e30f;
; #pragma unroll
;             for (int sb = 0; sb < 4; ++sb)
; #pragma unroll
;                 for (int j = 0; j < 4; ++j) t = fmaxf(t, s[ct][sb][j]);
;             t = fmaxf(t, __shfl_xor(t, 16)); t = fmaxf(t, __shfl_xor(t, 32));
;             tz[ct] = t; un[ct] = st.m[ct] < -1e29f;
;             nd[ct] = (t > -1e29f) && (t > ATT_THR || un[ct]);
.LBB0_1131:
	v_lshrrev_b64 v[60:61], s4, v[156:157]
	v_and_b32_e32 v60, 1, v60
	v_cmp_eq_u32_e64 s[70:71], 1, v60
	v_cmp_ne_u32_e32 vcc, 0, v60
	s_waitcnt lgkmcnt(0)
	s_barrier
	s_cbranch_vccz .LBB0_1157
	s_cmp_eq_u32 s4, s37
	s_mov_b64 s[0:1], -1
	s_cbranch_scc1 .LBB0_1152
	v_cmp_gt_f32_e64 s[0:1], s96, v190
	v_cmp_gt_f32_e64 s[4:5], s96, v191
	v_cndmask_b32_e64 v64, -v190, 0, s[0:1]
	v_cndmask_b32_e64 v60, -v191, 0, s[4:5]
	v_cndmask_b32_e64 v64, v227, v64, s[70:71]
	v_cndmask_b32_e64 v60, v227, v60, s[70:71]
	v_add3_u32 v198, v193, v164, v183
	ds_read_b128 v[68:71], v198
	ds_read_b128 v[72:75], v198 offset:2304
	ds_read_b128 v[76:79], v198 offset:4608
	ds_read_b128 v[80:83], v198 offset:6912
	ds_read_b128 v[84:87], v198 offset:64
	ds_read_b128 v[88:91], v198 offset:2368
	ds_read_b128 v[194:197], v198 offset:4672
	ds_read_b128 v[206:209], v198 offset:6976
	v_mov_b32_e32 v65, v64
	v_mov_b32_e32 v61, v60
	v_mov_b64_e32 v[66:67], v[64:65]
	v_mov_b64_e32 v[62:63], v[60:61]
	v_cmp_gt_f32_e64 s[0:1], s96, v190
	s_mov_b64 s[6:7], 0
	s_mov_b64 s[8:9], 0
	s_waitcnt lgkmcnt(7)
	v_mfma_f32_16x16x32_bf16 v[108:111], v[68:71], v[4:7], v[64:67]
	v_mfma_f32_16x16x32_bf16 v[96:99], v[68:71], v[12:15], v[60:63]
	s_waitcnt lgkmcnt(6)
	v_mfma_f32_16x16x32_bf16 v[116:119], v[72:75], v[4:7], v[64:67]
	v_mfma_f32_16x16x32_bf16 v[100:103], v[72:75], v[12:15], v[60:63]
	s_waitcnt lgkmcnt(5)
	v_mfma_f32_16x16x32_bf16 v[112:115], v[76:79], v[4:7], v[64:67]
	v_mfma_f32_16x16x32_bf16 v[92:95], v[76:79], v[12:15], v[60:63]
	s_waitcnt lgkmcnt(4)
	v_mfma_f32_16x16x32_bf16 v[120:123], v[80:83], v[4:7], v[64:67]
	v_mfma_f32_16x16x32_bf16 v[104:107], v[80:83], v[12:15], v[60:63]
	s_waitcnt lgkmcnt(3)
	v_mfma_f32_16x16x32_bf16 v[108:111], v[84:87], v[8:11], v[108:111]
	v_mfma_f32_16x16x32_bf16 v[96:99], v[84:87], v[16:19], v[96:99]
	s_waitcnt lgkmcnt(2)
	v_mfma_f32_16x16x32_bf16 v[116:119], v[88:91], v[8:11], v[116:119]
	v_mfma_f32_16x16x32_bf16 v[100:103], v[88:91], v[16:19], v[100:103]
	s_waitcnt lgkmcnt(1)
	v_mfma_f32_16x16x32_bf16 v[112:115], v[194:197], v[8:11], v[112:115]
	v_mfma_f32_16x16x32_bf16 v[92:95], v[194:197], v[16:19], v[92:95]
	s_waitcnt lgkmcnt(0)
	v_mfma_f32_16x16x32_bf16 v[120:123], v[206:209], v[8:11], v[120:123]
	v_mfma_f32_16x16x32_bf16 v[104:107], v[206:209], v[16:19], v[104:107]
	s_nop 3
	v_max3_f32 v60, v108, s36, v109
	v_max3_f32 v60, v60, v110, v111
	v_max3_f32 v60, v60, v116, v117
	v_max3_f32 v60, v60, v118, v119
	v_max3_f32 v60, v60, v112, v113
	v_max3_f32 v60, v60, v114, v115
	v_max3_f32 v60, v60, v120, v121
	v_max3_f32 v60, v60, v122, v123
	ds_bpermute_b32 v61, v185, v60
	s_waitcnt lgkmcnt(0)
	v_max_f32_e32 v60, v60, v61
	ds_bpermute_b32 v61, v153, v60
	s_waitcnt lgkmcnt(0)
	v_max_f32_e32 v203, v60, v61
	v_cmp_lt_f32_e32 vcc, s96, v203
	s_and_saveexec_b64 s[4:5], vcc
	s_cbranch_execz .LBB0_1145
	v_cmp_nlt_f32_e32 vcc, s95, v203
	s_mov_b64 s[8:9], -1
	s_and_saveexec_b64 s[10:11], vcc
	s_orn2_b64 s[8:9], s[0:1], exec
	s_or_b64 exec, exec, s[10:11]
	s_and_b64 s[8:9], s[8:9], exec
.LBB0_1145:
	s_or_b64 exec, exec, s[4:5]
	v_max3_f32 v60, v96, s36, v97
	v_max3_f32 v60, v60, v98, v99
	v_max3_f32 v60, v60, v100, v101
	v_max3_f32 v60, v60, v102, v103
	v_max3_f32 v60, v60, v92, v93
	v_max3_f32 v60, v60, v94, v95
	v_max3_f32 v60, v60, v104, v105
	v_max3_f32 v60, v60, v106, v107
	ds_bpermute_b32 v61, v185, v60
	v_cmp_gt_f32_e64 s[4:5], s96, v191
	s_waitcnt lgkmcnt(0)
	v_max_f32_e32 v60, v60, v61
	ds_bpermute_b32 v61, v153, v60
	s_waitcnt lgkmcnt(0)
	v_max_f32_e32 v204, v60, v61
	v_cmp_lt_f32_e32 vcc, s96, v204
	s_and_saveexec_b64 s[10:11], vcc
	s_cbranch_execz .LBB0_1149
	v_cmp_nlt_f32_e32 vcc, s95, v204
	s_mov_b64 s[6:7], -1
	s_and_saveexec_b64 s[12:13], vcc
	s_orn2_b64 s[6:7], s[4:5], exec
	s_or_b64 exec, exec, s[12:13]
	s_and_b64 s[6:7], s[6:7], exec
; #define LAS __attribute__((address_space(3)))
; __device__ __forceinline__ void attn_pv(AttnState& st, const LAS bf16_t* Vt, const bf16x8 (&pf)[2][2], int fr, int fq) {
;     const LAS bf16_t* vb = Vt + (4 * fq + (fr >> 2)) * KSTR + 4 * (fr & 3);
; #pragma unroll
;     for (int kg = 0; kg < 2; ++kg)
; #pragma unroll
;         for (int dt = 0; dt < 4; ++dt) {
;             const s16x4 v0 = __builtin_amdgcn_ds_read_tr16_b64_v4i16((LAS s16x4*)(vb + (kg * 32) * KSTR + dt * 16));
;             const s16x4 v1 = __builtin_amdgcn_ds_read_tr16_b64_v4i16((LAS s16x4*)(vb + (kg * 32 + 16) * KSTR + dt * 16));
;             const bf16x8 vf = {v0[0], v0[1], v0[2], v0[3], v1[0], v1[1], v1[2], v1[3]};
; template <int MODE, bool FAST, bool DEFER>
; __device__ __forceinline__ void attn_tile(AttnState& st, const LAS bf16_t* Ks, const LAS bf16_t* Vt, int jb, int tq, bool mybit, int fr, int fq, float (&imp)[16], float& prev_t3, bf16x8 (&pfo)[2][2]) {
;     ...
;         if (__builtin_amdgcn_ballot_w64(nd[0] || nd[1]) != 0ull) {
; #pragma unroll
;             for (int ct = 0; ct < 2; ++ct) {
;                 const float dl = nd[ct] ? tz[ct] : 0.f;
;                 const float alpha = nd[ct] ? (un[ct] ? 0.f : __builtin_amdgcn_exp2f(-tz[ct])) : 1.f;
;                 st.m[ct] = nd[ct] ? ((un[ct] ? 0.f : st.m[ct]) + tz[ct]) : st.m[ct];
;                 st.l[ct] *= alpha;
; #pragma unroll
;                 for (int dt = 0; dt < 4; ++dt) st.o[ct][dt] = st.o[ct][dt] * alpha;
; #pragma unroll
;                 for (int sb = 0; sb < 4; ++sb) s[ct][sb] = s[ct][sb] - dl;
;             }
;         }
; #pragma unroll
;         for (int ct = 0; ct < 2; ++ct) {
;             float ls = 0.f;
; #pragma unroll
;             for (int sb = 0; sb < 4; ++sb)
; #pragma unroll
;                 for (int j = 0; j < 4; ++j) { const float pe = __builtin_amdgcn_exp2f(s[ct][sb][j]); s[ct][sb][j] = pe; ls += pe; }
;             st.l[ct] += ls;
;         }
.LBB0_1149:
	s_or_b64 exec, exec, s[10:11]
	v_add3_u32 v248, s17, v167, v184
	ds_read_b64_tr_b16 v[68:69], v248 offset:18432
	ds_read_b64_tr_b16 v[70:71], v248 offset:20736
	ds_read_b64_tr_b16 v[72:73], v248 offset:18464
	ds_read_b64_tr_b16 v[74:75], v248 offset:20768
	ds_read_b64_tr_b16 v[76:77], v248 offset:18496
	ds_read_b64_tr_b16 v[78:79], v248 offset:20800
	ds_read_b64_tr_b16 v[80:81], v248 offset:18528
	ds_read_b64_tr_b16 v[82:83], v248 offset:20832
	ds_read_b64_tr_b16 v[210:211], v248 offset:23040
	ds_read_b64_tr_b16 v[212:213], v248 offset:25344
	ds_read_b64_tr_b16 v[230:231], v248 offset:23072
	ds_read_b64_tr_b16 v[232:233], v248 offset:25376
	ds_read_b64_tr_b16 v[234:235], v248 offset:23104
	ds_read_b64_tr_b16 v[236:237], v248 offset:25408
	ds_read_b64_tr_b16 v[238:239], v248 offset:23136
	ds_read_b64_tr_b16 v[240:241], v248 offset:25440
	s_or_b64 s[10:11], s[8:9], s[6:7]
	s_and_b64 vcc, exec, s[10:11]
	s_cbranch_vccz .LBB0_1151
	v_exp_f32_e64 v60, -v203
	v_exp_f32_e64 v215, -v204
	v_cndmask_b32_e64 v214, 0, v203, s[8:9]
	v_cndmask_b32_e64 v61, v190, 0, s[0:1]
	v_cndmask_b32_e64 v60, v60, 0, s[0:1]
	v_sub_f32_e32 v108, v108, v214
	v_sub_f32_e32 v109, v109, v214
	v_sub_f32_e32 v110, v110, v214
	v_sub_f32_e32 v111, v111, v214
	v_sub_f32_e32 v116, v116, v214
	v_sub_f32_e32 v117, v117, v214
	v_sub_f32_e32 v118, v118, v214
	v_sub_f32_e32 v119, v119, v214
	v_sub_f32_e32 v112, v112, v214
	v_sub_f32_e32 v113, v113, v214
	v_sub_f32_e32 v114, v114, v214
	v_sub_f32_e32 v115, v115, v214
	v_sub_f32_e32 v120, v120, v214
	v_sub_f32_e32 v121, v121, v214
	v_sub_f32_e32 v122, v122, v214
	v_sub_f32_e32 v123, v123, v214
	v_cndmask_b32_e64 v214, v215, 0, s[4:5]
	v_cndmask_b32_e64 v215, v191, 0, s[4:5]
	v_add_f32_e32 v61, v61, v203
	v_cndmask_b32_e64 v60, 1.0, v60, s[8:9]
	v_cndmask_b32_e64 v129, 0, v204, s[6:7]
	v_cndmask_b32_e64 v214, 1.0, v214, s[6:7]
	v_add_f32_e32 v215, v215, v204
	v_cndmask_b32_e64 v190, v190, v61, s[8:9]
	v_mul_f32_e32 v159, v159, v60
	v_pk_mul_f32 v[46:47], v[46:47], v[60:61] op_sel_hi:[1,0]
	v_pk_mul_f32 v[44:45], v[44:45], v[60:61] op_sel_hi:[1,0]
	v_pk_mul_f32 v[50:51], v[50:51], v[60:61] op_sel_hi:[1,0]
	v_pk_mul_f32 v[48:49], v[48:49], v[60:61] op_sel_hi:[1,0]
	v_pk_mul_f32 v[54:55], v[54:55], v[60:61] op_sel_hi:[1,0]
	v_pk_mul_f32 v[52:53], v[52:53], v[60:61] op_sel_hi:[1,0]
	v_pk_mul_f32 v[58:59], v[58:59], v[60:61] op_sel_hi:[1,0]
	v_pk_mul_f32 v[56:57], v[56:57], v[60:61] op_sel_hi:[1,0]
	v_cndmask_b32_e64 v191, v191, v215, s[6:7]
	v_mul_f32_e32 v158, v158, v214
	v_pk_mul_f32 v[30:31], v[30:31], v[214:215] op_sel_hi:[1,0]
	v_pk_mul_f32 v[28:29], v[28:29], v[214:215] op_sel_hi:[1,0]
	v_pk_mul_f32 v[34:35], v[34:35], v[214:215] op_sel_hi:[1,0]
	v_pk_mul_f32 v[32:33], v[32:33], v[214:215] op_sel_hi:[1,0]
	v_pk_mul_f32 v[26:27], v[26:27], v[214:215] op_sel_hi:[1,0]
	v_pk_mul_f32 v[24:25], v[24:25], v[214:215] op_sel_hi:[1,0]
	v_pk_mul_f32 v[22:23], v[22:23], v[214:215] op_sel_hi:[1,0]
	v_pk_mul_f32 v[20:21], v[20:21], v[214:215] op_sel_hi:[1,0]
	v_sub_f32_e32 v96, v96, v129
	v_sub_f32_e32 v97, v97, v129
	v_sub_f32_e32 v98, v98, v129
	v_sub_f32_e32 v99, v99, v129
	v_sub_f32_e32 v100, v100, v129
	v_sub_f32_e32 v101, v101, v129
	v_sub_f32_e32 v102, v102, v129
	v_sub_f32_e32 v103, v103, v129
	v_sub_f32_e32 v92, v92, v129
	v_sub_f32_e32 v93, v93, v129
	v_sub_f32_e32 v94, v94, v129
	v_sub_f32_e32 v95, v95, v129
	v_sub_f32_e32 v104, v104, v129
	v_sub_f32_e32 v105, v105, v129
	v_sub_f32_e32 v106, v106, v129
	v_sub_f32_e32 v107, v107, v129
.LBB0_1151:
	v_exp_f32_e32 v108, v108
	v_exp_f32_e32 v109, v109
	v_exp_f32_e32 v110, v110
	v_exp_f32_e32 v111, v111
	v_exp_f32_e32 v116, v116
	v_add_f32_e32 v129, v109, v108
	v_exp_f32_e32 v117, v117
	v_add_f32_e32 v129, v110, v129
	v_exp_f32_e32 v118, v118
	v_add_f32_e32 v129, v111, v129
	v_exp_f32_e32 v119, v119
	v_add_f32_e32 v129, v116, v129
	v_exp_f32_e32 v112, v112
	v_add_f32_e32 v129, v117, v129
	v_exp_f32_e32 v113, v113
	v_add_f32_e32 v129, v118, v129
	v_exp_f32_e32 v114, v114
	v_add_f32_e32 v129, v119, v129
	v_exp_f32_e32 v115, v115
	v_add_f32_e32 v129, v112, v129
	v_exp_f32_e32 v120, v120
	v_add_f32_e32 v129, v113, v129
	v_exp_f32_e32 v121, v121
	v_add_f32_e32 v129, v114, v129
	v_exp_f32_e32 v122, v122
	v_add_f32_e32 v129, v115, v129
	v_exp_f32_e32 v123, v123
	v_add_f32_e32 v129, v120, v129
	v_exp_f32_e32 v96, v96
	v_add_f32_e32 v129, v121, v129
	v_exp_f32_e32 v97, v97
	v_add_f32_e32 v129, v122, v129
	v_exp_f32_e32 v98, v98
	v_add_f32_e32 v129, v123, v129
	v_exp_f32_e32 v99, v99
	v_add_f32_e32 v159, v159, v129
	v_exp_f32_e32 v100, v100
	v_add_f32_e32 v129, v97, v96
	v_exp_f32_e32 v101, v101
	v_add_f32_e32 v129, v98, v129
	v_exp_f32_e32 v102, v102
	v_add_f32_e32 v129, v99, v129
	v_exp_f32_e32 v103, v103
	v_add_f32_e32 v129, v100, v129
	v_exp_f32_e32 v92, v92
	v_add_f32_e32 v129, v101, v129
	v_exp_f32_e32 v93, v93
	v_add_f32_e32 v129, v102, v129
	v_exp_f32_e32 v94, v94
	v_add_f32_e32 v129, v103, v129
	v_exp_f32_e32 v95, v95
	v_add_f32_e32 v129, v92, v129
	v_exp_f32_e32 v104, v104
	v_add_f32_e32 v129, v93, v129
	v_exp_f32_e32 v105, v105
	v_add_f32_e32 v129, v94, v129
	v_exp_f32_e32 v106, v106
	v_add_f32_e32 v129, v95, v129
	v_exp_f32_e32 v107, v107
	v_add_f32_e32 v129, v104, v129
	v_add_f32_e32 v129, v105, v129
	v_add_f32_e32 v129, v106, v129
	v_add_f32_e32 v203, v107, v129
	s_mov_b64 s[0:1], 0

; #define LAS __attribute__((address_space(3)))
; __device__ __forceinline__ void attn_pv(AttnState& st, const LAS bf16_t* Vt, const bf16x8 (&pf)[2][2], int fr, int fq) {
;     const LAS bf16_t* vb = Vt + (4 * fq + (fr >> 2)) * KSTR + 4 * (fr & 3);
; #pragma unroll
;     for (int kg = 0; kg < 2; ++kg)
; #pragma unroll
;         for (int dt = 0; dt < 4; ++dt) {
;             const s16x4 v0 = __builtin_amdgcn_ds_read_tr16_b64_v4i16((LAS s16x4*)(vb + (kg * 32) * KSTR + dt * 16));
;             const s16x4 v1 = __builtin_amdgcn_ds_read_tr16_b64_v4i16((LAS s16x4*)(vb + (kg * 32 + 16) * KSTR + dt * 16));
;             const bf16x8 vf = {v0[0], v0[1], v0[2], v0[3], v1[0], v1[1], v1[2], v1[3]};
; template <int MODE, bool FAST, bool DEFER>
; __device__ __forceinline__ void attn_tile(AttnState& st, const LAS bf16_t* Ks, const LAS bf16_t* Vt, int jb, int tq, bool mybit, int fr, int fq, float (&imp)[16], float& prev_t3, bf16x8 (&pfo)[2][2]) {
;     ...
; #pragma unroll
;     for (int ct = 0; ct < 2; ++ct) {
;         const float mu = (FAST && MODE == M_SLC && !mybit) ? 1e30f : st.m[ct];
;         float ls = 0.f;
; #pragma unroll
;         for (int sb = 0; sb < 4; ++sb)
; #pragma unroll
;             for (int j = 0; j < 4; ++j) {
;                 float pe = __builtin_amdgcn_exp2f(s[ct][sb][j] - mu);
;                 if (!FAST) pe = ((vbits >> (sb * 4 + j)) & 1u) ? pe : 0.f;
;                 s[ct][sb][j] = pe; ls += pe;
;             }
;         st.l[ct] += ls;
;     }
.LBB0_1155:
	v_sub_f32_e32 v91, v91, v190
	v_exp_f32_e32 v91, v91
	v_sub_f32_e32 v90, v90, v190
	v_exp_f32_e32 v90, v90
	v_sub_f32_e32 v89, v89, v190
	v_exp_f32_e32 v89, v89
	v_sub_f32_e32 v88, v88, v190
	v_exp_f32_e32 v88, v88
	v_sub_f32_e32 v87, v87, v190
	v_cndmask_b32_e64 v108, 0, v91, s[72:73]
	v_exp_f32_e32 v87, v87
	v_sub_f32_e32 v86, v86, v190
	v_cndmask_b32_e64 v109, 0, v90, s[96:97]
	v_add_f32_e32 v90, 0, v108
	v_exp_f32_e32 v86, v86
	v_sub_f32_e32 v85, v85, v190
	v_add_f32_e32 v90, v109, v90
	v_cndmask_b32_e64 v110, 0, v89, s[94:95]
	v_exp_f32_e32 v85, v85
	v_sub_f32_e32 v84, v84, v190
	v_add_f32_e32 v89, v110, v90
	v_cndmask_b32_e64 v111, 0, v88, s[8:9]
	v_exp_f32_e32 v84, v84
	v_sub_f32_e32 v83, v83, v190
	v_add_f32_e32 v88, v111, v89
	v_cndmask_b32_e64 v116, 0, v87, s[90:91]
	v_exp_f32_e32 v83, v83
	v_sub_f32_e32 v82, v82, v190
	v_add_f32_e32 v87, v116, v88
	v_cndmask_b32_e64 v117, 0, v86, s[92:93]
	v_exp_f32_e32 v82, v82
	v_sub_f32_e32 v79, v79, v190
	v_add_f32_e32 v86, v117, v87
	v_cndmask_b32_e64 v118, 0, v85, s[86:87]
	v_exp_f32_e32 v79, v79
	v_sub_f32_e32 v78, v78, v190
	v_add_f32_e32 v85, v118, v86
	v_cndmask_b32_e64 v119, 0, v84, s[88:89]
	v_exp_f32_e32 v78, v78
	v_sub_f32_e32 v75, v75, v190
	v_add_f32_e32 v84, v119, v85
	v_cndmask_b32_e64 v112, 0, v83, s[82:83]
	v_exp_f32_e32 v75, v75
	v_sub_f32_e32 v74, v74, v190
	v_add_f32_e32 v83, v112, v84
	v_cndmask_b32_e64 v113, 0, v82, s[84:85]
	v_exp_f32_e32 v74, v74
	v_sub_f32_e32 v71, v71, v190
	v_add_f32_e32 v82, v113, v83
	v_cndmask_b32_e64 v114, 0, v79, s[78:79]
	v_exp_f32_e32 v71, v71
	v_sub_f32_e32 v70, v70, v190
	v_add_f32_e32 v79, v114, v82
	v_cndmask_b32_e64 v115, 0, v78, s[80:81]
	v_exp_f32_e32 v70, v70
	v_add_f32_e32 v78, v115, v79
	v_cndmask_b32_e64 v120, 0, v75, s[74:75]
	v_add_f32_e32 v75, v120, v78
	v_cndmask_b32_e64 v121, 0, v74, s[76:77]
	v_add_f32_e32 v74, v121, v75
	v_cndmask_b32_e64 v122, v71, 0, s[70:71]
	v_add_f32_e32 v71, v122, v74
	v_cndmask_b32_e64 v123, v70, 0, s[4:5]
	v_add_f32_e32 v70, v123, v71
	v_sub_f32_e32 v71, v81, v191
	v_exp_f32_e32 v71, v71
	v_sub_f32_e32 v74, v80, v191
	v_exp_f32_e32 v74, v74
	v_sub_f32_e32 v72, v72, v191
	v_cndmask_b32_e64 v96, 0, v71, s[72:73]
	v_sub_f32_e32 v71, v77, v191
	v_exp_f32_e32 v71, v71
	v_cndmask_b32_e64 v97, 0, v74, s[96:97]
	v_sub_f32_e32 v74, v76, v191
	v_exp_f32_e32 v74, v74
	v_cndmask_b32_e64 v98, 0, v71, s[94:95]
	v_sub_f32_e32 v71, v73, v191
	v_exp_f32_e32 v71, v71
	v_add_f32_e32 v159, v159, v70
	v_add_f32_e32 v70, 0, v96
	v_exp_f32_e32 v72, v72
	v_sub_f32_e32 v69, v69, v191
	v_add_f32_e32 v70, v97, v70
	v_exp_f32_e32 v69, v69
	v_sub_f32_e32 v68, v68, v191
	v_add_f32_e32 v70, v98, v70
	v_cndmask_b32_e64 v99, 0, v74, s[8:9]
	v_exp_f32_e32 v68, v68
	v_sub_f32_e32 v67, v67, v191
	v_add_f32_e32 v70, v99, v70
	v_cndmask_b32_e64 v100, 0, v71, s[90:91]
	v_exp_f32_e32 v67, v67
	v_sub_f32_e32 v66, v66, v191
	v_add_f32_e32 v70, v100, v70
	v_cndmask_b32_e64 v101, 0, v72, s[92:93]
	v_exp_f32_e32 v66, v66
	v_sub_f32_e32 v65, v65, v191
	v_add_f32_e32 v70, v101, v70
	v_cndmask_b32_e64 v102, 0, v69, s[86:87]
	v_exp_f32_e32 v65, v65
	v_sub_f32_e32 v64, v64, v191
	v_add_f32_e32 v69, v102, v70
	v_cndmask_b32_e64 v103, 0, v68, s[88:89]
	v_exp_f32_e32 v64, v64
	v_sub_f32_e32 v63, v63, v191
	v_add_f32_e32 v68, v103, v69
	v_cndmask_b32_e64 v92, 0, v67, s[82:83]
	v_exp_f32_e32 v63, v63
	v_sub_f32_e32 v62, v62, v191
	v_add_f32_e32 v67, v92, v68
	v_cndmask_b32_e64 v93, 0, v66, s[84:85]
	v_exp_f32_e32 v62, v62
	v_sub_f32_e32 v61, v61, v191
	v_add_f32_e32 v66, v93, v67
	v_cndmask_b32_e64 v94, 0, v65, s[78:79]
	v_exp_f32_e32 v61, v61
	v_sub_f32_e32 v60, v60, v191
	v_add_f32_e32 v65, v94, v66
	v_cndmask_b32_e64 v95, 0, v64, s[80:81]
	v_exp_f32_e32 v60, v60
	v_add_f32_e32 v64, v95, v65
	v_cndmask_b32_e64 v104, 0, v63, s[74:75]
	v_add_f32_e32 v63, v104, v64
	v_cndmask_b32_e64 v105, 0, v62, s[76:77]
	v_add_f32_e32 v62, v105, v63
	v_cndmask_b32_e64 v106, v61, 0, s[70:71]
	v_add_f32_e32 v61, v106, v62
	v_cndmask_b32_e64 v107, v60, 0, s[4:5]
	v_readlane_b32 s72, v253, 63
	v_readlane_b32 s76, v254, 23
	v_add_f32_e32 v203, v107, v61
	v_readlane_b32 s75, v254, 2
	v_readlane_b32 s86, v254, 33
	v_readlane_b32 s87, v254, 34
	v_readlane_b32 s92, v254, 3
	v_readlane_b32 s73, v254, 0
	v_readlane_b32 s74, v254, 1
	v_readlane_b32 s77, v254, 24
	v_readlane_b32 s78, v254, 25
	v_readlane_b32 s79, v254, 26
	v_readlane_b32 s80, v254, 27
	v_readlane_b32 s81, v254, 28
	v_readlane_b32 s82, v254, 29
	v_readlane_b32 s83, v254, 30
	v_readlane_b32 s84, v254, 31
	v_readlane_b32 s85, v254, 32
	v_readlane_b32 s88, v254, 35
	v_readlane_b32 s89, v254, 36
	v_readlane_b32 s90, v254, 37
	v_readlane_b32 s91, v254, 38
	v_readlane_b32 s93, v254, 4
	v_readlane_b32 s75, v254, 7
	s_movk_i32 s86, 0x2400
	s_movk_i32 s87, 0xc00
	s_mov_b32 s94, 0x800000
	s_mov_b32 s95, 0x40c00000
	s_mov_b32 s96, 0xefa18f08
	v_readlane_b32 s97, v254, 39
	v_add3_u32 v248, s17, v167, v184
	ds_read_b64_tr_b16 v[68:69], v248 offset:18432
	ds_read_b64_tr_b16 v[70:71], v248 offset:20736
	ds_read_b64_tr_b16 v[72:73], v248 offset:18464
	ds_read_b64_tr_b16 v[74:75], v248 offset:20768
	ds_read_b64_tr_b16 v[76:77], v248 offset:18496
	ds_read_b64_tr_b16 v[78:79], v248 offset:20800
	ds_read_b64_tr_b16 v[80:81], v248 offset:18528
	ds_read_b64_tr_b16 v[82:83], v248 offset:20832
	ds_read_b64_tr_b16 v[210:211], v248 offset:23040
	ds_read_b64_tr_b16 v[212:213], v248 offset:25344
	ds_read_b64_tr_b16 v[230:231], v248 offset:23072
	ds_read_b64_tr_b16 v[232:233], v248 offset:25376
	ds_read_b64_tr_b16 v[234:235], v248 offset:23104
	ds_read_b64_tr_b16 v[236:237], v248 offset:25408
	ds_read_b64_tr_b16 v[238:239], v248 offset:23136
	ds_read_b64_tr_b16 v[240:241], v248 offset:25440
; __device__ __forceinline__ unsigned cvt_pk_bf16(float lo, float hi) { const f32x2c v = {lo, hi}; const bf16x2c r = __builtin_convertvector(v, bf16x2c); return __builtin_bit_cast(unsigned, r); }
; template <int MODE, bool FAST, bool DEFER>
; __device__ __forceinline__ void attn_tile(AttnState& st, const LAS bf16_t* Ks, const LAS bf16_t* Vt, int jb, int tq, bool mybit, int fr, int fq, float (&imp)[16], float& prev_t3, bf16x8 (&pfo)[2][2]) {
;     ...
;     if (MODE != M_CMP1) {
; #pragma unroll
;         for (int kg = 0; kg < 2; ++kg)
; #pragma unroll
;             for (int ct = 0; ct < 2; ++ct) { u32x4v w; w.x = cvt_pk_bf16(s[ct][2 * kg][0], s[ct][2 * kg][1]); w.y = cvt_pk_bf16(s[ct][2 * kg][2], s[ct][2 * kg][3]);
;                 w.z = cvt_pk_bf16(s[ct][2 * kg + 1][0], s[ct][2 * kg + 1][1]); w.w = cvt_pk_bf16(s[ct][2 * kg + 1][2], s[ct][2 * kg + 1][3]); pfo[kg][ct] = __builtin_bit_cast(bf16x8, w); }
;         if (!DEFER) attn_pv(st, Vt, pfo, fr, fq);
; template <int MODE>
; __device__ __forceinline__ void attn_branch(AttnState& st, const bf16_t* __restrict__ Kg, const bf16_t* __restrict__ Vg, u64 tiles, LAS bf16_t* KsB, LAS bf16_t* VtB,
;                                             int tq, u64 mymask, int cur, int fr, int fq, float (&imp)[16]) {
;     ...
;         if (jn < 0) break;
;         jb = jn; pb ^= 1; vb = vb == 2 ? 0 : vb + 1;
.LBB0_1156:
	v_cvt_pk_bf16_f32 v84, v108, v109
	v_cvt_pk_bf16_f32 v85, v110, v111
	v_cvt_pk_bf16_f32 v86, v116, v117
	v_cvt_pk_bf16_f32 v87, v118, v119
	v_cvt_pk_bf16_f32 v88, v96, v97
	v_cvt_pk_bf16_f32 v89, v98, v99
	v_cvt_pk_bf16_f32 v90, v100, v101
	v_cvt_pk_bf16_f32 v91, v102, v103
	v_cvt_pk_bf16_f32 v60, v112, v113
	v_cvt_pk_bf16_f32 v61, v114, v115
	v_cvt_pk_bf16_f32 v62, v120, v121
	v_cvt_pk_bf16_f32 v63, v122, v123
	v_cvt_pk_bf16_f32 v64, v92, v93
	v_cvt_pk_bf16_f32 v65, v94, v95
	v_cvt_pk_bf16_f32 v66, v104, v105
	v_cvt_pk_bf16_f32 v67, v106, v107
	v_add_f32_e32 v158, v158, v203
	s_waitcnt lgkmcnt(0)
	v_mfma_f32_16x16x32_bf16 v[44:47], v[68:71], v[84:87], v[44:47]
	v_mfma_f32_16x16x32_bf16 v[28:31], v[68:71], v[88:91], v[28:31]
	v_mfma_f32_16x16x32_bf16 v[48:51], v[72:75], v[84:87], v[48:51]
	v_mfma_f32_16x16x32_bf16 v[32:35], v[72:75], v[88:91], v[32:35]
	v_mfma_f32_16x16x32_bf16 v[52:55], v[76:79], v[84:87], v[52:55]
	v_mfma_f32_16x16x32_bf16 v[24:27], v[76:79], v[88:91], v[24:27]
	v_mfma_f32_16x16x32_bf16 v[56:59], v[80:83], v[84:87], v[56:59]
	v_mfma_f32_16x16x32_bf16 v[20:23], v[80:83], v[88:91], v[20:23]
	v_mfma_f32_16x16x32_bf16 v[44:47], v[210:213], v[60:63], v[44:47]
	v_mfma_f32_16x16x32_bf16 v[28:31], v[210:213], v[64:67], v[28:31]
	v_mfma_f32_16x16x32_bf16 v[48:51], v[230:233], v[60:63], v[48:51]
	v_mfma_f32_16x16x32_bf16 v[32:35], v[230:233], v[64:67], v[32:35]
	v_mfma_f32_16x16x32_bf16 v[52:55], v[234:237], v[60:63], v[52:55]
	v_mfma_f32_16x16x32_bf16 v[24:27], v[234:237], v[64:67], v[24:27]
	v_mfma_f32_16x16x32_bf16 v[56:59], v[238:241], v[60:63], v[56:59]
	v_mfma_f32_16x16x32_bf16 v[20:23], v[238:241], v[64:67], v[20:23]
	s_branch .LBB0_1158
.LBB0_1157:
.LBB0_1158:
	s_cmp_gt_i32 s16, -1
	s_cselect_b64 s[0:1], -1, 0
	s_cselect_b32 s70, 0x2400, 0
	v_xor_b32_e32 v193, s70, v193
	s_add_i32 s4, s15, 1
	s_cmp_lg_u32 s15, 2
	s_mov_b64 s[70:71], 0x80
	s_cselect_b32 s15, s4, 0
	s_and_b64 vcc, exec, s[0:1]
	s_cbranch_vccz .LBB0_1160
	s_mov_b32 s4, s16
	s_mov_b64 s[0:1], s[2:3]
	s_branch .LBB0_1128
